# phase-0 bf16 x / layer-0 weight stores non-temporal
# baseline (speedup 1.0000x reference)
; #define LAS __attribute__((address_space(3)))
; __device__ __forceinline__ unsigned pk2(float lo, float hi) { f32x2_t v = {lo, hi}; bf16x2_t b = __builtin_convertvector(v, bf16x2_t); return __builtin_bit_cast(unsigned, b); }
; __device__ __forceinline__ void transpose_item(const float* W, int K, int N, bf16* WT, const float* scale, LAS float* scr, int item, int lane) {
;     ...
;         for (int i = 0; i < 8; ++i) { const int kk = 8 * i + r; f32x4 x = v[i]; if (scale) x = x * scale[k0 + kk];
;             scr[kk * 33 + 4 * q + 0] = x[0]; scr[kk * 33 + 4 * q + 1] = x[1]; scr[kk * 33 + 4 * q + 2] = x[2]; scr[kk * 33 + 4 * q + 3] = x[3]; }
;     }
;     asm volatile("s_waitcnt lgkmcnt(0)" ::: "memory");
;     const int c = lane & 7;
; #pragma unroll
;     for (int j = 0; j < 4; ++j) { const int n = (lane >> 3) + 8 * j; const LAS float* s = scr + (8 * c) * 33 + n;
;         v4u o; o.x = pk2(s[0 * 33], s[1 * 33]); o.y = pk2(s[2 * 33], s[3 * 33]); o.z = pk2(s[4 * 33], s[5 * 33]); o.w = pk2(s[6 * 33], s[7 * 33]);
;         *(v4u*)(WT + (size_t)(n0 + n) * K + k0 + 8 * c) = o; }
;     asm volatile("s_waitcnt lgkmcnt(0)" ::: "memory");
.LBB0_8:
	s_waitcnt vmcnt(1)
	v_add_u32_e32 v2, 0x18c0, v48
	ds_write2_b32 v2, v16, v17 offset1:1
	v_add_u32_e32 v2, 0x18c8, v48
	ds_write2_b32 v2, v14, v15 offset1:1
	v_add_u32_e32 v2, 0x1ce0, v48
	ds_write2_b32 v2, v10, v11 offset1:1
	v_add_u32_e32 v2, 0x1ce8, v48
	ds_write2_b32 v2, v12, v13 offset1:1
	s_waitcnt lgkmcnt(0)
	s_sub_i32 s12, 0, s17
	s_waitcnt vmcnt(0)
	ds_read2_b32 v[6:7], v1 offset0:33 offset1:41
	ds_read2_b32 v[8:9], v1 offset1:8
	ds_read2_b32 v[10:11], v1 offset0:66 offset1:74
	ds_read2_b32 v[12:13], v1 offset0:99 offset1:107
	ds_read2_b32 v[14:15], v1 offset0:132 offset1:140
	ds_read2_b32 v[16:17], v1 offset0:165 offset1:173
	ds_read2_b32 v[18:19], v1 offset0:198 offset1:206
	ds_read2_b32 v[20:21], v1 offset0:231 offset1:239
	s_add_i32 s12, s12, s14
	v_add_u32_e32 v24, s12, v38
	v_ashrrev_i32_e32 v25, 31, v24
	v_lshl_add_u64 v[22:23], s[10:11], 1, v[42:43]
	v_lshlrev_b64 v[26:27], 11, v[24:25]
	s_waitcnt lgkmcnt(6)
	v_cvt_pk_bf16_f32 v2, v8, v6
	s_waitcnt lgkmcnt(4)
	v_cvt_pk_bf16_f32 v3, v10, v12
	s_waitcnt lgkmcnt(2)
	v_cvt_pk_bf16_f32 v4, v14, v16
	s_waitcnt lgkmcnt(0)
	v_cvt_pk_bf16_f32 v5, v18, v20
	v_lshl_add_u64 v[26:27], v[22:23], 0, v[26:27]
	v_add_u32_e32 v6, 8, v24
	global_store_dwordx4 v[26:27], v[2:5], off nt
	s_add_i32 s16, s16, s28
	s_add_i32 s14, s14, s15
	v_cvt_pk_bf16_f32 v2, v9, v7
	v_ashrrev_i32_e32 v7, 31, v6
	v_cvt_pk_bf16_f32 v3, v11, v13
	v_cvt_pk_bf16_f32 v4, v15, v17
	v_cvt_pk_bf16_f32 v5, v19, v21
	v_lshlrev_b64 v[6:7], 11, v[6:7]
	ds_read2_b32 v[8:9], v1 offset0:49 offset1:57
	ds_read2_b32 v[10:11], v1 offset0:16 offset1:24
	ds_read2_b32 v[12:13], v1 offset0:82 offset1:90
	ds_read2_b32 v[14:15], v1 offset0:115 offset1:123
	ds_read2_b32 v[16:17], v1 offset0:148 offset1:156
	ds_read2_b32 v[18:19], v1 offset0:181 offset1:189
	ds_read2_b32 v[20:21], v1 offset0:214 offset1:222
	ds_read2_b32 v[26:27], v1 offset0:247 offset1:255
	v_lshl_add_u64 v[6:7], v[22:23], 0, v[6:7]
	global_store_dwordx4 v[6:7], v[2:5], off nt
	v_add_u32_e32 v6, 16, v24
	v_ashrrev_i32_e32 v7, 31, v6
	v_lshlrev_b64 v[6:7], 11, v[6:7]
	s_waitcnt lgkmcnt(6)
	v_cvt_pk_bf16_f32 v2, v10, v8
	s_waitcnt lgkmcnt(4)
	v_cvt_pk_bf16_f32 v3, v12, v14
	s_waitcnt lgkmcnt(2)
	v_cvt_pk_bf16_f32 v4, v16, v18
	s_waitcnt lgkmcnt(0)
	v_cvt_pk_bf16_f32 v5, v20, v26
	v_lshl_add_u64 v[6:7], v[22:23], 0, v[6:7]
	global_store_dwordx4 v[6:7], v[2:5], off nt
	v_add_u32_e32 v6, 24, v24
	v_ashrrev_i32_e32 v7, 31, v6
	v_lshlrev_b64 v[6:7], 11, v[6:7]
	v_cvt_pk_bf16_f32 v2, v11, v9
	v_cvt_pk_bf16_f32 v3, v13, v15
	v_cvt_pk_bf16_f32 v4, v17, v19
	v_cvt_pk_bf16_f32 v5, v21, v27
	v_lshl_add_u64 v[6:7], v[22:23], 0, v[6:7]
	global_store_dwordx4 v[6:7], v[2:5], off nt
	s_waitcnt lgkmcnt(0)
	s_cmpk_lt_i32 s16, 0x800
	s_cbranch_scc0 .LBB0_25

; #define LAS __attribute__((address_space(3)))
; __device__ __forceinline__ unsigned pk2(float lo, float hi) { f32x2_t v = {lo, hi}; bf16x2_t b = __builtin_convertvector(v, bf16x2_t); return __builtin_bit_cast(unsigned, b); }
; __device__ __forceinline__ void transpose_item(const float* W, int K, int N, bf16* WT, const float* scale, LAS float* scr, int item, int lane) {
;     const int nblk = N / 32, kb = item / nblk, nb = item % nblk, k0 = 64 * kb, n0 = 32 * nb;
;     {
;         const int q = lane & 7, r = lane >> 3;
;         f32x4 v[8];
; #pragma unroll
;         for (int i = 0; i < 8; ++i) v[i] = *(const f32x4*)(W + (size_t)(k0 + 8 * i + r) * N + n0 + 4 * q);
; #pragma unroll
;         for (int i = 0; i < 8; ++i) { const int kk = 8 * i + r; f32x4 x = v[i]; if (scale) x = x * scale[k0 + kk];
;             scr[kk * 33 + 4 * q + 0] = x[0]; scr[kk * 33 + 4 * q + 1] = x[1]; scr[kk * 33 + 4 * q + 2] = x[2]; scr[kk * 33 + 4 * q + 3] = x[3]; }
;     }
;     asm volatile("s_waitcnt lgkmcnt(0)" ::: "memory");
;     const int c = lane & 7;
; #pragma unroll
;     for (int j = 0; j < 4; ++j) { const int n = (lane >> 3) + 8 * j; const LAS float* s = scr + (8 * c) * 33 + n;
;         v4u o; o.x = pk2(s[0 * 33], s[1 * 33]); o.y = pk2(s[2 * 33], s[3 * 33]); o.z = pk2(s[4 * 33], s[5 * 33]); o.w = pk2(s[6 * 33], s[7 * 33]);
;         *(v4u*)(WT + (size_t)(n0 + n) * K + k0 + 8 * c) = o; }
;     asm volatile("s_waitcnt lgkmcnt(0)" ::: "memory");
.LBB0_27:
	s_ashr_i32 s4, s14, 31
	s_lshr_b32 s4, s4, 27
	s_add_i32 s4, s14, s4
	s_ashr_i32 s5, s4, 5
	s_lshl_b32 s4, s5, 6
	s_lshl_b32 s5, s5, 10
	v_or_b32_e32 v22, s4, v1
	s_sub_i32 s10, s12, s5
	v_or_b32_e32 v24, 8, v22
	s_ashr_i32 s11, s10, 31
	v_ashrrev_i32_e32 v23, 31, v22
	v_or_b32_e32 v26, 16, v22
	v_or_b32_e32 v28, 24, v22
	v_or_b32_e32 v30, 32, v22
	v_or_b32_e32 v32, 40, v22
	v_or_b32_e32 v34, 48, v22
	v_or_b32_e32 v36, 56, v22
	v_ashrrev_i32_e32 v25, 31, v24
	v_lshl_add_u64 v[38:39], s[10:11], 2, v[2:3]
	v_lshlrev_b64 v[22:23], 12, v[22:23]
	v_ashrrev_i32_e32 v27, 31, v26
	v_ashrrev_i32_e32 v29, 31, v28
	v_ashrrev_i32_e32 v31, 31, v30
	v_ashrrev_i32_e32 v33, 31, v32
	v_ashrrev_i32_e32 v35, 31, v34
	v_ashrrev_i32_e32 v37, 31, v36
	v_lshlrev_b64 v[40:41], 12, v[24:25]
	v_lshl_add_u64 v[22:23], v[38:39], 0, v[22:23]
	v_lshlrev_b64 v[26:27], 12, v[26:27]
	v_lshlrev_b64 v[28:29], 12, v[28:29]
	v_lshlrev_b64 v[30:31], 12, v[30:31]
	v_lshlrev_b64 v[32:33], 12, v[32:33]
	v_lshlrev_b64 v[34:35], 12, v[34:35]
	v_lshlrev_b64 v[36:37], 12, v[36:37]
	v_lshl_add_u64 v[54:55], v[38:39], 0, v[40:41]
	global_load_dwordx4 v[22:25], v[22:23], off nt
	v_lshl_add_u64 v[56:57], v[38:39], 0, v[26:27]
	v_lshl_add_u64 v[58:59], v[38:39], 0, v[28:29]
	v_lshl_add_u64 v[60:61], v[38:39], 0, v[30:31]
	v_lshl_add_u64 v[62:63], v[38:39], 0, v[32:33]
	v_lshl_add_u64 v[64:65], v[38:39], 0, v[34:35]
	v_lshl_add_u64 v[66:67], v[38:39], 0, v[36:37]
	global_load_dwordx4 v[26:29], v[54:55], off nt
	global_load_dwordx4 v[30:33], v[56:57], off nt
	global_load_dwordx4 v[34:37], v[58:59], off nt
	global_load_dwordx4 v[38:41], v[60:61], off nt
	global_load_dwordx4 v[42:45], v[62:63], off nt
	global_load_dwordx4 v[46:49], v[64:65], off nt
	global_load_dwordx4 v[50:53], v[66:67], off nt
	v_add_u32_e32 v56, s10, v1
	v_add_u32_e32 v58, 8, v56
	v_add_u32_e32 v60, 16, v56
	v_add_u32_e32 v62, 24, v56
	s_ashr_i32 s5, s4, 31
	v_ashrrev_i32_e32 v57, 31, v56
	v_ashrrev_i32_e32 v59, 31, v58
	v_ashrrev_i32_e32 v61, 31, v60
	v_ashrrev_i32_e32 v63, 31, v62
	v_lshl_add_u64 v[54:55], s[4:5], 1, v[4:5]
	v_lshlrev_b64 v[56:57], 11, v[56:57]
	v_lshlrev_b64 v[58:59], 11, v[58:59]
	v_lshlrev_b64 v[60:61], 11, v[60:61]
	v_lshlrev_b64 v[62:63], 11, v[62:63]
	v_lshl_add_u64 v[56:57], v[54:55], 0, v[56:57]
	v_lshl_add_u64 v[58:59], v[54:55], 0, v[58:59]
	v_lshl_add_u64 v[60:61], v[54:55], 0, v[60:61]
	v_lshl_add_u64 v[54:55], v[54:55], 0, v[62:63]
	s_add_i32 s14, s14, s28
	s_add_i32 s12, s12, s13
	s_cmpk_lt_i32 s14, 0x200
	s_waitcnt vmcnt(7)
	ds_write2_b32 v7, v22, v23 offset1:1
	ds_write2_b32 v7, v24, v25 offset0:2 offset1:3
	s_waitcnt vmcnt(6)
	ds_write2_b32 v8, v26, v27 offset1:1
	ds_write2_b32 v9, v28, v29 offset1:1
	s_waitcnt vmcnt(5)
	ds_write2_b32 v10, v30, v31 offset1:1
	ds_write2_b32 v11, v32, v33 offset1:1
	s_waitcnt vmcnt(4)
	ds_write2_b32 v12, v34, v35 offset1:1
	ds_write2_b32 v13, v36, v37 offset1:1
	s_waitcnt vmcnt(3)
	ds_write2_b32 v14, v38, v39 offset1:1
	ds_write2_b32 v15, v40, v41 offset1:1
	s_waitcnt vmcnt(2)
	ds_write2_b32 v16, v42, v43 offset1:1
	ds_write2_b32 v17, v44, v45 offset1:1
	s_waitcnt vmcnt(1)
	ds_write2_b32 v18, v46, v47 offset1:1
	ds_write2_b32 v19, v48, v49 offset1:1
	s_waitcnt vmcnt(0)
	ds_write2_b32 v20, v50, v51 offset1:1
	ds_write2_b32 v21, v52, v53 offset1:1
	s_waitcnt lgkmcnt(0)
	ds_read2_b32 v[24:25], v6 offset0:33 offset1:41
	ds_read2_b32 v[26:27], v6 offset1:8
	ds_read2_b32 v[28:29], v6 offset0:66 offset1:74
	ds_read2_b32 v[30:31], v6 offset0:99 offset1:107
	ds_read2_b32 v[32:33], v6 offset0:132 offset1:140
	ds_read2_b32 v[34:35], v6 offset0:165 offset1:173
	ds_read2_b32 v[36:37], v6 offset0:198 offset1:206
	ds_read2_b32 v[38:39], v6 offset0:231 offset1:239
	ds_read2_b32 v[40:41], v6 offset0:49 offset1:57
	ds_read2_b32 v[42:43], v6 offset0:16 offset1:24
	ds_read2_b32 v[44:45], v6 offset0:82 offset1:90
	ds_read2_b32 v[46:47], v6 offset0:115 offset1:123
	ds_read2_b32 v[48:49], v6 offset0:148 offset1:156
	ds_read2_b32 v[50:51], v6 offset0:181 offset1:189
	ds_read2_b32 v[52:53], v6 offset0:214 offset1:222
	ds_read2_b32 v[62:63], v6 offset0:247 offset1:255
	s_waitcnt lgkmcnt(14)
	v_cvt_pk_bf16_f32 v22, v26, v24
	s_waitcnt lgkmcnt(12)
	v_cvt_pk_bf16_f32 v23, v28, v30
	v_cvt_pk_bf16_f32 v26, v27, v25
	s_waitcnt lgkmcnt(10)
	v_cvt_pk_bf16_f32 v24, v32, v34
	s_waitcnt lgkmcnt(8)
	v_cvt_pk_bf16_f32 v25, v36, v38
	v_cvt_pk_bf16_f32 v27, v29, v31
	v_cvt_pk_bf16_f32 v28, v33, v35
	v_cvt_pk_bf16_f32 v29, v37, v39
	s_waitcnt lgkmcnt(6)
	v_cvt_pk_bf16_f32 v30, v42, v40
	s_waitcnt lgkmcnt(4)
	v_cvt_pk_bf16_f32 v31, v44, v46
	s_waitcnt lgkmcnt(2)
	v_cvt_pk_bf16_f32 v32, v48, v50
	s_waitcnt lgkmcnt(0)
	v_cvt_pk_bf16_f32 v33, v52, v62
	v_cvt_pk_bf16_f32 v34, v43, v41
	v_cvt_pk_bf16_f32 v35, v45, v47
	v_cvt_pk_bf16_f32 v36, v49, v51
	v_cvt_pk_bf16_f32 v37, v53, v63
	global_store_dwordx4 v[56:57], v[22:25], off nt
	global_store_dwordx4 v[58:59], v[26:29], off nt
	global_store_dwordx4 v[60:61], v[30:33], off nt
	global_store_dwordx4 v[54:55], v[34:37], off nt
	s_waitcnt lgkmcnt(0)
	s_cbranch_scc1 .LBB0_27
	s_mov_b32 s14, s51

; __device__ __forceinline__ unsigned pk2(float lo, float hi) { f32x2_t v = {lo, hi}; bf16x2_t b = __builtin_convertvector(v, bf16x2_t); return __builtin_bit_cast(unsigned, b); }
; __global__ void __launch_bounds__(NTHREADS, 2) fwd_megakernel(Args A) {
;     ...
;     for (int m = 2 * gw; m < MROWS; m += 2 * NGW) {
;         const f32x4* xr = (const f32x4*)(A.x + (size_t)m * DM) + 2 * lane; v4u* o16 = (v4u*)(XB + (size_t)m * DM) + lane; float s0 = 0.f, s1 = 0.f;
;         f32x4 va[4], vb[4];
; #pragma unroll
;         for (int j = 0; j < 2; ++j) { va[2 * j] = xr[128 * j]; va[2 * j + 1] = xr[128 * j + 1]; vb[2 * j] = xr[256 + 128 * j]; vb[2 * j + 1] = xr[256 + 128 * j + 1]; }
; #pragma unroll
;         for (int j = 0; j < 4; ++j) { s0 += (va[j][0] * va[j][0] + va[j][1] * va[j][1]) + (va[j][2] * va[j][2] + va[j][3] * va[j][3]); s1 += (vb[j][0] * vb[j][0] + vb[j][1] * vb[j][1]) + (vb[j][2] * vb[j][2] + vb[j][3] * vb[j][3]); }
; #pragma unroll
;         for (int j = 0; j < 2; ++j) {
;             o16[64 * j] = (v4u){pk2(va[2 * j][0], va[2 * j][1]), pk2(va[2 * j][2], va[2 * j][3]), pk2(va[2 * j + 1][0], va[2 * j + 1][1]), pk2(va[2 * j + 1][2], va[2 * j + 1][3])};
;             o16[128 + 64 * j] = (v4u){pk2(vb[2 * j][0], vb[2 * j][1]), pk2(vb[2 * j][2], vb[2 * j][3]), pk2(vb[2 * j + 1][0], vb[2 * j + 1][1]), pk2(vb[2 * j + 1][2], vb[2 * j + 1][3])};
;         }
; #pragma unroll
;         for (int o = 1; o < 64; o <<= 1) { s0 += __shfl_xor(s0, o); s1 += __shfl_xor(s1, o); }
;         if (lane == 0) { ssq[m] = s0; ssq[m + 1] = s1; }
.LBB0_32:
	v_add_co_u32_e32 v38, vcc, 0xfffff000, v6
	v_lshl_add_u64 v[42:43], v[6:7], 0, s[22:23]
	s_nop 0
	v_addc_co_u32_e32 v39, vcc, -1, v7, vcc
	s_waitcnt lgkmcnt(0)
	global_load_dwordx4 v[8:11], v[6:7], off offset:-2064 nt
	global_load_dwordx4 v[18:21], v[6:7], off offset:-16 nt
	global_load_dwordx4 v[22:25], v[6:7], off nt
	global_load_dwordx4 v[26:29], v[6:7], off offset:-2048 nt
	global_load_dwordx4 v[30:33], v[38:39], off offset:-16 nt
	global_load_dwordx4 v[34:37], v[6:7], off offset:-4096 nt
	s_nop 0
	global_load_dwordx4 v[38:41], v[38:39], off offset:-2064 nt
	s_waitcnt vmcnt(6)
	v_mov_b32_e32 v55, v11
	global_load_dwordx4 v[42:45], v[42:43], off offset:16 nt
	s_waitcnt vmcnt(6)
	v_cvt_pk_bf16_f32 v46, v18, v19
	v_cvt_pk_bf16_f32 v47, v20, v21
	s_waitcnt vmcnt(5)
	v_cvt_pk_bf16_f32 v48, v22, v23
	v_cvt_pk_bf16_f32 v49, v24, v25
	v_mov_b32_e32 v57, v18
	v_mov_b32_e32 v59, v20
	v_mov_b32_e32 v61, v22
	v_mov_b32_e32 v63, v24
	s_waitcnt vmcnt(4)
	v_mov_b32_e32 v67, v27
	v_mov_b32_e32 v71, v29
	v_mov_b32_e32 v73, v9
	s_waitcnt vmcnt(3)
	v_mov_b32_e32 v18, v31
	v_mov_b32_e32 v20, v33
	s_waitcnt vmcnt(2)
	v_mov_b32_e32 v22, v35
	v_mov_b32_e32 v24, v37
	s_waitcnt vmcnt(1)
	v_mov_b32_e32 v54, v41
	v_mov_b32_e32 v72, v39
	v_mov_b32_e32 v53, v10
	v_mov_b32_e32 v65, v26
	v_mov_b32_e32 v69, v28
	v_mov_b32_e32 v52, v40
	v_mov_b32_e32 v56, v30
	v_mov_b32_e32 v58, v32
	v_mov_b32_e32 v60, v34
	v_cvt_pk_bf16_f32 v50, v38, v39
	v_mov_b32_e32 v39, v8
	v_mov_b32_e32 v62, v36
	v_pk_mul_f32 v[18:19], v[18:19], v[18:19]
	v_pk_mul_f32 v[20:21], v[20:21], v[20:21]
	v_pk_mul_f32 v[22:23], v[22:23], v[22:23]
	v_pk_mul_f32 v[24:25], v[24:25], v[24:25]
	v_pk_mul_f32 v[54:55], v[54:55], v[54:55]
	v_pk_mul_f32 v[72:73], v[72:73], v[72:73]
	v_pk_fma_f32 v[52:53], v[52:53], v[52:53], v[54:55]
	v_pk_fma_f32 v[18:19], v[56:57], v[56:57], v[18:19]
	v_pk_fma_f32 v[20:21], v[58:59], v[58:59], v[20:21]
	v_pk_fma_f32 v[22:23], v[60:61], v[60:61], v[22:23]
	v_pk_fma_f32 v[24:25], v[62:63], v[62:63], v[24:25]
	v_pk_fma_f32 v[38:39], v[38:39], v[38:39], v[72:73]
	v_pk_add_f32 v[18:19], v[18:19], v[20:21]
	v_pk_add_f32 v[20:21], v[22:23], v[24:25]
	v_pk_add_f32 v[22:23], v[38:39], v[52:53]
	v_cvt_pk_bf16_f32 v8, v8, v9
	v_cvt_pk_bf16_f32 v9, v10, v11
	v_cvt_pk_bf16_f32 v10, v26, v27
	v_cvt_pk_bf16_f32 v11, v28, v29
	v_cvt_pk_bf16_f32 v51, v40, v41
	s_waitcnt vmcnt(0)
	v_mov_b32_e32 v66, v43
	v_mov_b32_e32 v70, v45
	v_mov_b32_e32 v64, v42
	v_mov_b32_e32 v68, v44
	v_pk_mul_f32 v[66:67], v[66:67], v[66:67]
	v_pk_mul_f32 v[70:71], v[70:71], v[70:71]
	v_pk_fma_f32 v[54:55], v[64:65], v[64:65], v[66:67]
	v_pk_fma_f32 v[64:65], v[68:69], v[68:69], v[70:71]
	v_cvt_pk_bf16_f32 v52, v42, v43
	v_pk_add_f32 v[54:55], v[54:55], v[64:65]
	v_cvt_pk_bf16_f32 v53, v44, v45
	v_pk_add_f32 v[22:23], v[22:23], v[54:55]
	s_nop 0
	v_pk_add_f32 v[18:19], v[22:23], v[18:19]
	v_lshl_add_u64 v[22:23], s[82:83], 0, v[2:3]
	v_pk_add_f32 v[18:19], v[18:19], v[20:21]
	ds_bpermute_b32 v20, v1, v18
	ds_bpermute_b32 v21, v1, v19
	v_add_co_u32_e32 v22, vcc, s11, v22
	s_waitcnt lgkmcnt(0)
	v_pk_add_f32 v[18:19], v[18:19], v[20:21]
	ds_bpermute_b32 v20, v13, v18
	ds_bpermute_b32 v21, v13, v19
	v_addc_co_u32_e32 v23, vcc, 0, v23, vcc
	global_store_dwordx4 v[22:23], v[8:11], off offset:2048 nt
	global_store_dwordx4 v[22:23], v[50:53], off nt
	s_waitcnt lgkmcnt(0)
	v_pk_add_f32 v[18:19], v[18:19], v[20:21]
	ds_bpermute_b32 v20, v14, v18
	ds_bpermute_b32 v21, v14, v19
	s_waitcnt lgkmcnt(0)
	v_pk_add_f32 v[18:19], v[18:19], v[20:21]
	ds_bpermute_b32 v20, v15, v18
	ds_bpermute_b32 v21, v15, v19
	s_waitcnt lgkmcnt(0)
	v_pk_add_f32 v[8:9], v[18:19], v[20:21]
	ds_bpermute_b32 v10, v16, v8
	ds_bpermute_b32 v11, v16, v9
	v_cvt_pk_bf16_f32 v18, v30, v31
	v_cvt_pk_bf16_f32 v19, v32, v33
	v_cvt_pk_bf16_f32 v20, v34, v35
	v_cvt_pk_bf16_f32 v21, v36, v37
	s_waitcnt lgkmcnt(0)
	v_pk_add_f32 v[8:9], v[8:9], v[10:11]
	ds_bpermute_b32 v10, v17, v8
	ds_bpermute_b32 v11, v17, v9
	global_store_dwordx4 v[22:23], v[18:21], off offset:1024 nt
	global_store_dwordx4 v[22:23], v[46:49], off offset:3072 nt
	s_and_saveexec_b64 s[24:25], s[4:5]
	s_cbranch_execz .LBB0_31
	s_add_u32 s26, s82, s14
	s_addc_u32 s27, s83, s15
	s_waitcnt lgkmcnt(0)
	v_pk_add_f32 v[8:9], v[8:9], v[10:11]
	global_store_dwordx2 v5, v[8:9], s[26:27]
	s_branch .LBB0_31
